# fnet gemm_tile: step 1's LDS-DMA pieces issued in the prologue behind step 0's
# baseline (speedup 1.0000x reference)
; DI int otid() { int t = threadIdx.x; asm volatile("" : "+v"(t)); return t; }
; #define G_WAIT() { asm volatile("s_waitcnt vmcnt(0)" ::: "memory"); __syncthreads(); }
;   const int tid_full = otid(); const int tid = tid_full & 255; lds += (tid_full >> 8) * HALF_LDS;
;   const int lane = tid & 63, w = tid >> 6, l31 = lane & 31, h = lane >> 5;
;   const int wr = w >> 1, wc = w & 1;
;   const int lrow = tid >> 3, lch = (tid & 7) ^ ((tid >> 4) & 7);
;   const bf16_t* ag = A + (size_t)lrow * lda + lch * 8;
;   const bf16_t* bg = Bt + (size_t)lrow * ldb + lch * 8;
;   const size_t a32 = (size_t)32 * lda, b32 = (size_t)32 * ldb;
;   f32x16 acc[2][2];
; #pragma unroll
;   for (int i = 0; i < 2; ++i)
; #pragma unroll
;     for (int j = 0; j < 2; ++j)
; #pragma unroll
;       for (int e = 0; e < 16; ++e) acc[i][j][e] = 0.f;
;   const int nk = K >> 6;
;   const int rsw = (l31 >> 1) & 7;
;   const int aoff = (wr * 64 + l31) * 128, boff = 16384 + (wc * 64 + l31) * 128;
;   char* ldst = lds + tid * 16;
;     ...
;   G_DMA(0, 0);
;   G_WAIT();
;   for (int kt = 0; kt < nk; kt += 2) {
;     if (kt + 1 < nk) G_DMA(1, kt + 1);
;     G_COMPUTE(0);
; DI void phase_mix(KP p, int l, char* lds) {
;     ...
;       const int m0 = mt * 128, n0 = nt * 128;
;       gemm_tile(YD + (size_t)m0 * 256, 256, wf + (size_t)n0 * 256, 256, 256, lds, [&](int m, int n, f32x4 v) {
.LBB0_151:
	s_or_b64 exec, exec, s[4:5]
	s_lshl_b32 s2, s2, 7
	s_lshl_b32 s4, s46, 7
	s_and_b32 s5, s4, 0x80
	s_lshl_b64 s[18:19], s[2:3], 9
	v_readlane_b32 s4, v255, 38
	s_add_u32 s18, s4, s18
	v_readlane_b32 s4, v255, 39
	v_mov_b32_e32 v71, v196
	s_barrier
	s_addc_u32 s19, s4, s19
	s_lshl_b32 s4, s5, 9
	v_readlane_b32 s20, v255, 40
	s_add_u32 s20, s20, s4
	v_lshrrev_b32_e32 v0, 4, v71
	v_readlane_b32 s4, v255, 41
	v_xor_b32_e32 v8, v0, v71
	v_lshlrev_b32_e32 v0, 6, v71
	s_addc_u32 s21, s4, 0
	v_and_b32_e32 v0, 0x3e00, v0
	v_lshrrev_b32_e32 v70, 8, v71
	s_mov_b32 s55, 0x11000
	v_lshl_add_u64 v[2:3], s[20:21], 0, v[0:1]
	v_lshl_add_u64 v[4:5], s[18:19], 0, v[0:1]
	v_lshlrev_b32_e32 v0, 4, v8
	v_and_b32_e32 v6, 0xff, v71
	v_mad_i32_i24 v73, v70, s55, 0
	v_and_b32_e32 v0, 0x70, v0
	v_lshl_add_u64 v[66:67], v[2:3], 0, v[0:1]
	v_lshlrev_b32_e32 v2, 7, v71
	v_lshl_add_u32 v94, v6, 4, v73
	v_lshl_add_u64 v[68:69], v[4:5], 0, v[0:1]
	v_and_b32_e32 v4, 0x2f80, v2
	v_add_u32_e32 v2, 0x4000, v94
	v_readfirstlane_b32 s36, v94
	s_mov_b32 m0, s36
	v_readfirstlane_b32 s20, v2
	v_add_u32_e32 v5, 0x1000, v94
	global_load_lds_dwordx4 v[68:69], off
	s_mov_b32 m0, s20
	s_mov_b64 s[18:19], 0x4000
	v_readfirstlane_b32 s4, v5
	global_load_lds_dwordx4 v[66:67], off
	v_lshl_add_u64 v[2:3], v[68:69], 0, s[18:19]
	s_mov_b32 m0, s4
	v_add_u32_e32 v5, 0x5000, v94
	global_load_lds_dwordx4 v[2:3], off
	v_lshl_add_u64 v[2:3], v[66:67], 0, s[18:19]
	v_readfirstlane_b32 s19, v5
	v_add_u32_e32 v5, 0x2000, v94
	s_mov_b32 m0, s19
	s_mov_b64 s[34:35], 0x8000
	v_readfirstlane_b32 s18, v5
	global_load_lds_dwordx4 v[2:3], off
	v_lshl_add_u64 v[2:3], v[68:69], 0, s[34:35]
	s_mov_b32 m0, s18
	v_add_u32_e32 v5, 0x6000, v94
	global_load_lds_dwordx4 v[2:3], off
	v_lshl_add_u64 v[2:3], v[66:67], 0, s[34:35]
	v_readfirstlane_b32 s34, v5
	v_add_u32_e32 v5, 0x3000, v94
	s_mov_b32 m0, s34
	s_mov_b64 s[40:41], 0xc000
	v_readfirstlane_b32 s21, v5
	v_add_u32_e32 v5, 0x7000, v94
	global_load_lds_dwordx4 v[2:3], off
	v_lshl_add_u64 v[2:3], v[68:69], 0, s[40:41]
	s_mov_b32 m0, s21
	v_readfirstlane_b32 s35, v5
	v_lshrrev_b32_e32 v7, 5, v71
	global_load_lds_dwordx4 v[2:3], off
	v_lshl_add_u64 v[2:3], v[66:67], 0, s[40:41]
	s_mov_b32 m0, s35
	v_bfe_u32 v95, v71, 1, 3
	global_load_lds_dwordx4 v[2:3], off
	v_add_u32_e32 v250, 0x8000, v94
	s_mov_b64 s[76:77], 0x80
	v_readfirstlane_b32 s74, v250
	v_lshl_add_u64 v[248:249], v[68:69], 0, s[76:77]
	s_mov_b32 m0, s74
	s_nop 0
	global_load_lds_dwordx4 v[248:249], off
	v_add_u32_e32 v250, 0xc000, v94
	s_mov_b64 s[76:77], 0x80
	v_readfirstlane_b32 s74, v250
	v_lshl_add_u64 v[248:249], v[66:67], 0, s[76:77]
	s_mov_b32 m0, s74
	s_nop 0
	global_load_lds_dwordx4 v[248:249], off
	v_add_u32_e32 v250, 0x9000, v94
	s_mov_b64 s[76:77], 0x4080
	v_readfirstlane_b32 s74, v250
	v_lshl_add_u64 v[248:249], v[68:69], 0, s[76:77]
	s_mov_b32 m0, s74
	s_nop 0
	global_load_lds_dwordx4 v[248:249], off
	v_add_u32_e32 v250, 0xd000, v94
	s_mov_b64 s[76:77], 0x4080
	v_readfirstlane_b32 s74, v250
	v_lshl_add_u64 v[248:249], v[66:67], 0, s[76:77]
	s_mov_b32 m0, s74
	s_nop 0
	global_load_lds_dwordx4 v[248:249], off
	v_add_u32_e32 v250, 0xa000, v94
	s_mov_b64 s[76:77], 0x8080
	v_readfirstlane_b32 s74, v250
	v_lshl_add_u64 v[248:249], v[68:69], 0, s[76:77]
	s_mov_b32 m0, s74
	s_nop 0
	global_load_lds_dwordx4 v[248:249], off
	v_add_u32_e32 v250, 0xe000, v94
	s_mov_b64 s[76:77], 0x8080
	v_readfirstlane_b32 s74, v250
	v_lshl_add_u64 v[248:249], v[66:67], 0, s[76:77]
	s_mov_b32 m0, s74
	s_nop 0
	global_load_lds_dwordx4 v[248:249], off
	v_add_u32_e32 v250, 0xb000, v94
	s_mov_b64 s[76:77], 0xc080
	v_readfirstlane_b32 s74, v250
	v_lshl_add_u64 v[248:249], v[68:69], 0, s[76:77]
	s_mov_b32 m0, s74
	s_nop 0
	global_load_lds_dwordx4 v[248:249], off
	v_add_u32_e32 v250, 0xf000, v94
	s_mov_b64 s[76:77], 0xc080
	v_readfirstlane_b32 s74, v250
	v_lshl_add_u64 v[248:249], v[66:67], 0, s[76:77]
	s_mov_b32 m0, s74
	s_nop 0
	global_load_lds_dwordx4 v[248:249], off
	v_bitop3_b32 v2, v7, v95, 1 bitop3:0x6c
	v_lshlrev_b32_e32 v6, 4, v2
	v_add_u32_e32 v96, v73, v4
	v_add_u32_e32 v97, v96, v6
	s_waitcnt vmcnt(0)
	s_waitcnt vmcnt(0) lgkmcnt(0)
	s_barrier
	ds_read_b128 v[2:5], v97 offset:16384
	v_and_b32_e32 v72, 31, v71
	v_lshrrev_b32_e32 v0, 1, v71
	v_and_or_b32 v0, v0, 64, v72
	v_lshl_add_u32 v98, v0, 7, v73
	v_add_u32_e32 v99, v98, v6
	ds_read_b128 v[6:9], v99
	ds_read_b128 v[10:13], v99 offset:4096
	ds_read_b128 v[14:17], v97 offset:20480
	v_bfe_u32 v100, v71, 5, 1
	s_waitcnt lgkmcnt(2)
	v_mfma_f32_32x32x16_bf16 v[50:65], v[2:5], v[6:9], 0
	v_add_u32_e32 v103, 0x8000, v94
	v_add_u32_e32 v104, 0xc000, v94
	v_readfirstlane_b32 s37, v103
	v_lshl_add_u64 v[90:91], v[68:69], 0, s[28:29]
	s_mov_b32 m0, s37
	s_mov_b64 s[50:51], 0x4080
	v_readfirstlane_b32 s41, v104
	s_waitcnt lgkmcnt(1)
	v_mfma_f32_32x32x16_bf16 v[18:33], v[2:5], v[10:13], 0
	v_bitop3_b32 v2, v100, v95, 2 bitop3:0x36
	v_lshlrev_b32_e32 v78, 4, v2
	v_add_u32_e32 v101, v96, v78
	ds_read_b128 v[74:77], v101 offset:16384
	v_add_u32_e32 v102, v98, v78
	ds_read_b128 v[78:81], v102
	ds_read_b128 v[82:85], v102 offset:4096
	ds_read_b128 v[86:89], v101 offset:20480
	v_lshl_add_u64 v[92:93], v[66:67], 0, s[28:29]
	s_waitcnt lgkmcnt(4)
	v_mfma_f32_32x32x16_bf16 v[34:49], v[14:17], v[6:9], 0
	s_mov_b64 s[52:53], 0x8080
	s_mov_b64 s[56:57], 0xc080
	v_mul_u32_u24_e32 v0, 0x210, v0
	v_mfma_f32_32x32x16_bf16 v[2:17], v[14:17], v[10:13], 0
	s_waitcnt lgkmcnt(2)
	v_mfma_f32_32x32x16_bf16 v[50:65], v[74:77], v[78:81], v[50:65]
	s_waitcnt lgkmcnt(1)
	v_mfma_f32_32x32x16_bf16 v[18:33], v[74:77], v[82:85], v[18:33]
	v_bitop3_b32 v74, v100, v95, 4 bitop3:0x36
	s_waitcnt lgkmcnt(0)
; #define G_WAIT() { asm volatile("s_waitcnt vmcnt(0)" ::: "memory"); __syncthreads(); }
;     ...
;   G_DMA(0, 0);
;   G_WAIT();
;   for (int kt = 0; kt < nk; kt += 2) {
;     if (kt + 1 < nk) G_DMA(1, kt + 1);
;     G_COMPUTE(0);
;     G_WAIT();
;     if (kt + 1 < nk) {
;       if (kt + 2 < nk) G_DMA(0, kt + 2);
;       G_COMPUTE(1);
;       G_WAIT();
;     }
;   }
	v_mfma_f32_32x32x16_bf16 v[34:49], v[86:89], v[78:81], v[34:49]
	v_lshlrev_b32_e32 v78, 4, v74
	v_add_u32_e32 v105, v96, v78
	ds_read_b128 v[74:77], v105 offset:16384
	v_add_u32_e32 v106, v98, v78
	ds_read_b128 v[78:81], v106
	v_mfma_f32_32x32x16_bf16 v[2:17], v[86:89], v[82:85], v[2:17]
	ds_read_b128 v[82:85], v106 offset:4096
	ds_read_b128 v[86:89], v105 offset:20480
	v_lshl_add_u64 v[90:91], v[66:67], 0, s[50:51]
	s_mov_b32 m0, s41
	s_nop 0
	s_waitcnt lgkmcnt(0)
	v_mfma_f32_32x32x16_bf16 v[50:65], v[74:77], v[78:81], v[50:65]
	v_mfma_f32_32x32x16_bf16 v[18:33], v[74:77], v[82:85], v[18:33]
	v_add_u32_e32 v74, 0xd000, v94
	v_mfma_f32_32x32x16_bf16 v[34:49], v[86:89], v[78:81], v[34:49]
	v_lshl_add_u64 v[78:79], v[68:69], 0, s[50:51]
	v_readfirstlane_b32 s50, v74
	v_bitop3_b32 v74, v100, v95, 6 bitop3:0x36
	v_lshlrev_b32_e32 v74, 4, v74
	v_add_u32_e32 v80, 0x9000, v94
	v_add_u32_e32 v93, v96, v74
	v_readfirstlane_b32 s40, v80
	v_add_u32_e32 v92, v98, v74
	ds_read_b128 v[74:77], v93 offset:16384
	s_mov_b32 m0, s40
	v_mfma_f32_32x32x16_bf16 v[2:17], v[86:89], v[82:85], v[2:17]
	s_mov_b32 m0, s50
	ds_read_b128 v[78:81], v92
	ds_read_b128 v[82:85], v92 offset:4096
	ds_read_b128 v[86:89], v93 offset:20480
	v_add_u32_e32 v95, 0xa000, v94
	v_lshl_add_u64 v[90:91], v[68:69], 0, s[52:53]
	v_readfirstlane_b32 s51, v95
	s_mov_b32 m0, s51
	v_add_u32_e32 v95, 0xe000, v94
	s_waitcnt lgkmcnt(0)
	v_mfma_f32_32x32x16_bf16 v[50:65], v[74:77], v[78:81], v[50:65]
	v_lshl_add_u64 v[90:91], v[66:67], 0, s[52:53]
	v_readfirstlane_b32 s53, v95
	s_mov_b32 m0, s53
	s_nop 0
	v_mfma_f32_32x32x16_bf16 v[34:49], v[86:89], v[78:81], v[34:49]
	v_add_u32_e32 v80, 0xb000, v94
	v_lshl_add_u64 v[78:79], v[68:69], 0, s[56:57]
	v_readfirstlane_b32 s52, v80
	s_mov_b32 m0, s52
	v_lshl_add_u64 v[90:91], v[66:67], 0, s[22:23]
	v_mfma_f32_32x32x16_bf16 v[18:33], v[74:77], v[82:85], v[18:33]
	v_add_u32_e32 v76, 0xf000, v94
	v_lshl_add_u64 v[74:75], v[66:67], 0, s[56:57]
	v_readfirstlane_b32 s54, v76
	s_mov_b32 m0, s54
	s_mov_b64 s[56:57], 0x4100
	v_mfma_f32_32x32x16_bf16 v[2:17], v[86:89], v[82:85], v[2:17]
	s_waitcnt vmcnt(0)
	s_waitcnt vmcnt(0) lgkmcnt(0)
	s_barrier
	ds_read_b128 v[74:77], v97 offset:49152
	ds_read_b128 v[78:81], v99 offset:32768
	ds_read_b128 v[82:85], v99 offset:36864
	ds_read_b128 v[86:89], v97 offset:53248
	s_mov_b32 m0, s36
	s_waitcnt lgkmcnt(2)
	v_mfma_f32_32x32x16_bf16 v[50:65], v[74:77], v[78:81], v[50:65]
	s_waitcnt lgkmcnt(1)
	v_mfma_f32_32x32x16_bf16 v[18:33], v[74:77], v[82:85], v[18:33]
	s_waitcnt lgkmcnt(0)
	v_mfma_f32_32x32x16_bf16 v[34:49], v[86:89], v[78:81], v[34:49]
	v_mfma_f32_32x32x16_bf16 v[2:17], v[86:89], v[82:85], v[2:17]
	ds_read_b128 v[74:77], v101 offset:49152
	ds_read_b128 v[78:81], v102 offset:32768
	ds_read_b128 v[82:85], v102 offset:36864
	ds_read_b128 v[86:89], v101 offset:53248
	s_waitcnt lgkmcnt(2)
	v_mfma_f32_32x32x16_bf16 v[50:65], v[74:77], v[78:81], v[50:65]
	s_waitcnt lgkmcnt(1)
	v_mfma_f32_32x32x16_bf16 v[18:33], v[74:77], v[82:85], v[18:33]
	s_waitcnt lgkmcnt(0)
	v_mfma_f32_32x32x16_bf16 v[34:49], v[86:89], v[78:81], v[34:49]
	v_mfma_f32_32x32x16_bf16 v[2:17], v[86:89], v[82:85], v[2:17]
	ds_read_b128 v[74:77], v105 offset:49152
	ds_read_b128 v[78:81], v106 offset:32768
	ds_read_b128 v[82:85], v106 offset:36864
	ds_read_b128 v[86:89], v105 offset:53248
	s_waitcnt lgkmcnt(2)
	v_mfma_f32_32x32x16_bf16 v[50:65], v[74:77], v[78:81], v[50:65]
	s_waitcnt lgkmcnt(1)
	v_mfma_f32_32x32x16_bf16 v[18:33], v[74:77], v[82:85], v[18:33]
	v_lshl_add_u64 v[74:75], v[68:69], 0, s[22:23]
	global_load_lds_dwordx4 v[74:75], off
	ds_read_b128 v[74:77], v93 offset:49152
	s_mov_b32 m0, s20
	s_nop 0
	global_load_lds_dwordx4 v[90:91], off
	s_waitcnt lgkmcnt(0)
	v_mfma_f32_32x32x16_bf16 v[34:49], v[86:89], v[78:81], v[34:49]
	ds_read_b128 v[78:81], v92 offset:32768
	v_lshl_add_u64 v[90:91], v[68:69], 0, s[56:57]
	s_mov_b32 m0, s4
	s_lshl_b32 s4, s5, 1
	v_mfma_f32_32x32x16_bf16 v[2:17], v[86:89], v[82:85], v[2:17]
	ds_read_b128 v[82:85], v92 offset:36864
	ds_read_b128 v[86:89], v93 offset:53248
	global_load_lds_dwordx4 v[90:91], off
	v_lshl_add_u64 v[90:91], v[66:67], 0, s[56:57]
	s_mov_b32 m0, s19
	s_mov_b64 s[56:57], 0x8100
	global_load_lds_dwordx4 v[90:91], off
	v_lshl_add_u64 v[90:91], v[68:69], 0, s[56:57]
	s_mov_b32 m0, s18
	s_waitcnt lgkmcnt(0)
	v_mfma_f32_32x32x16_bf16 v[50:65], v[74:77], v[78:81], v[50:65]
	global_load_lds_dwordx4 v[90:91], off
	s_mov_b32 m0, s34
	s_mov_b64 s[18:19], 0xc100
	v_mfma_f32_32x32x16_bf16 v[34:49], v[86:89], v[78:81], v[34:49]
	v_lshl_add_u64 v[78:79], v[66:67], 0, s[56:57]
	global_load_lds_dwordx4 v[78:79], off
	v_lshl_add_u64 v[78:79], v[68:69], 0, s[18:19]
	s_mov_b32 m0, s21
	s_nop 0
	global_load_lds_dwordx4 v[78:79], off
	v_mfma_f32_32x32x16_bf16 v[18:33], v[74:77], v[82:85], v[18:33]
	v_lshl_add_u64 v[74:75], v[66:67], 0, s[18:19]
	s_mov_b32 m0, s35
	s_mov_b64 s[18:19], 0x180
	global_load_lds_dwordx4 v[74:75], off
	s_waitcnt vmcnt(0)
	s_waitcnt vmcnt(0) lgkmcnt(0)
	v_mfma_f32_32x32x16_bf16 v[2:17], v[86:89], v[82:85], v[2:17]
	s_barrier
; DI float silu(float x) { return x / (1.f + __expf(-x)); }
; DI f32x4 unpack4(u32x2 v) { f32x4 r = {bflo(v.x), bfhi(v.x), bflo(v.y), bfhi(v.y)}; return r; }
; DI u32x2 pack4(f32x4 v) { u32x2 r = {cvtpk(v[0], v[1]), cvtpk(v[2], v[3])}; return r; }
; #define G_WAIT() { asm volatile("s_waitcnt vmcnt(0)" ::: "memory"); __syncthreads(); }
;     ...
;   G_DMA(0, 0);
;   G_WAIT();
;   for (int kt = 0; kt < nk; kt += 2) {
;     if (kt + 1 < nk) G_DMA(1, kt + 1);
;     G_COMPUTE(0);
;     G_WAIT();
;     if (kt + 1 < nk) {
;       if (kt + 2 < nk) G_DMA(0, kt + 2);
;       G_COMPUTE(1);
;       G_WAIT();
;     }
;   }
;     ...
;   float* ct = (float*)lds;
; #pragma unroll
;   for (int i = 0; i < 2; ++i)
; #pragma unroll
;     for (int j = 0; j < 2; ++j)
; #pragma unroll
;       for (int q = 0; q < 4; ++q) {
;         f32x4 v = {acc[i][j][4 * q], acc[i][j][4 * q + 1], acc[i][j][4 * q + 2], acc[i][j][4 * q + 3]};
;         *(f32x4*)(ct + (wr * 64 + i * 32 + l31) * 132 + wc * 64 + j * 32 + 8 * q + 4 * h) = v;
;       }
;   __syncthreads();
; #pragma unroll 4
;   for (int it = 0; it < 16; ++it) {
;     const int idx = it * 256 + tid; const int row = idx >> 5, c4 = (idx & 31) * 4;
;     f32x4 v = *(const f32x4*)(ct + row * 132 + c4);
;     epi(row, c4, v);
;   }
; DI void phase_mix(KP p, int l, char* lds) {
;     ...
;       gemm_tile(YD + (size_t)m0 * 256, 256, wf + (size_t)n0 * 256, 256, 256, lds, [&](int m, int n, f32x4 v) {
;         const size_t r = (size_t)m0 + m;
;         f32x4 gd = unpack4(*(const u32x2*)(P + r * NIN + O_GD + n0 + n));
;         f32x4 o = {v[0] * silu(gd[0]), v[1] * silu(gd[1]), v[2] * silu(gd[2]), v[3] * silu(gd[3])};
;         *(u32x2*)(Y + r * 1024 + 768 + n0 + n) = pack4(o); });
	ds_read_b128 v[74:77], v97 offset:16384
	ds_read_b128 v[78:81], v99
	ds_read_b128 v[82:85], v99 offset:4096
	ds_read_b128 v[86:89], v97 offset:20480
	s_mov_b32 m0, s37
	v_lshl_add_u64 v[90:91], v[66:67], 0, s[18:19]
	s_waitcnt lgkmcnt(2)
	v_mfma_f32_32x32x16_bf16 v[50:65], v[74:77], v[78:81], v[50:65]
	s_waitcnt lgkmcnt(1)
	v_mfma_f32_32x32x16_bf16 v[18:33], v[74:77], v[82:85], v[18:33]
	s_waitcnt lgkmcnt(0)
	v_mfma_f32_32x32x16_bf16 v[34:49], v[86:89], v[78:81], v[34:49]
	v_mfma_f32_32x32x16_bf16 v[2:17], v[86:89], v[82:85], v[2:17]
	ds_read_b128 v[74:77], v101 offset:16384
	ds_read_b128 v[78:81], v102
	ds_read_b128 v[82:85], v102 offset:4096
	ds_read_b128 v[86:89], v101 offset:20480
	s_waitcnt lgkmcnt(2)
	v_mfma_f32_32x32x16_bf16 v[50:65], v[74:77], v[78:81], v[50:65]
	s_waitcnt lgkmcnt(1)
	v_mfma_f32_32x32x16_bf16 v[18:33], v[74:77], v[82:85], v[18:33]
	s_waitcnt lgkmcnt(0)
	v_mfma_f32_32x32x16_bf16 v[34:49], v[86:89], v[78:81], v[34:49]
	v_mfma_f32_32x32x16_bf16 v[2:17], v[86:89], v[82:85], v[2:17]
	ds_read_b128 v[74:77], v105 offset:16384
	ds_read_b128 v[78:81], v106
	ds_read_b128 v[82:85], v106 offset:4096
	ds_read_b128 v[86:89], v105 offset:20480
	s_waitcnt lgkmcnt(2)
	v_mfma_f32_32x32x16_bf16 v[50:65], v[74:77], v[78:81], v[50:65]
	s_waitcnt lgkmcnt(1)
	v_mfma_f32_32x32x16_bf16 v[18:33], v[74:77], v[82:85], v[18:33]
	v_lshl_add_u64 v[74:75], v[68:69], 0, s[18:19]
	global_load_lds_dwordx4 v[74:75], off
	ds_read_b128 v[74:77], v93 offset:16384
	s_mov_b32 m0, s41
	s_mov_b64 s[18:19], 0x4180
	global_load_lds_dwordx4 v[90:91], off
	s_waitcnt lgkmcnt(0)
	v_mfma_f32_32x32x16_bf16 v[34:49], v[86:89], v[78:81], v[34:49]
	ds_read_b128 v[78:81], v92
	v_lshl_add_u64 v[90:91], v[68:69], 0, s[18:19]
	s_mov_b32 m0, s40
	v_mfma_f32_32x32x16_bf16 v[2:17], v[86:89], v[82:85], v[2:17]
	ds_read_b128 v[82:85], v92 offset:4096
	ds_read_b128 v[86:89], v93 offset:20480
	global_load_lds_dwordx4 v[90:91], off
	v_lshl_add_u64 v[90:91], v[66:67], 0, s[18:19]
	s_mov_b32 m0, s50
	s_mov_b64 s[18:19], 0x8180
	global_load_lds_dwordx4 v[90:91], off
	v_lshl_add_u64 v[90:91], v[68:69], 0, s[18:19]
	s_mov_b32 m0, s51
	s_waitcnt lgkmcnt(0)
	v_mfma_f32_32x32x16_bf16 v[50:65], v[74:77], v[78:81], v[50:65]
	global_load_lds_dwordx4 v[90:91], off
	s_mov_b32 m0, s53
	v_mfma_f32_32x32x16_bf16 v[34:49], v[86:89], v[78:81], v[34:49]
	v_lshl_add_u64 v[78:79], v[66:67], 0, s[18:19]
	s_mov_b64 s[18:19], 0xc180
	global_load_lds_dwordx4 v[78:79], off
	v_lshl_add_u64 v[68:69], v[68:69], 0, s[18:19]
	s_mov_b32 m0, s52
	v_lshl_add_u64 v[66:67], v[66:67], 0, s[18:19]
	global_load_lds_dwordx4 v[68:69], off
	s_mov_b32 m0, s54
	v_mfma_f32_32x32x16_bf16 v[2:17], v[86:89], v[82:85], v[2:17]
	global_load_lds_dwordx4 v[66:67], off
	s_waitcnt vmcnt(0)
	s_waitcnt vmcnt(0) lgkmcnt(0)
	s_barrier
	v_and_b32_e32 v86, 64, v71
	v_mfma_f32_32x32x16_bf16 v[18:33], v[74:77], v[82:85], v[18:33]
	ds_read_b128 v[66:69], v97 offset:49152
	ds_read_b128 v[74:77], v99 offset:32768
	ds_read_b128 v[78:81], v99 offset:36864
	ds_read_b128 v[82:85], v97 offset:53248
	v_lshl_add_u32 v73, v86, 2, v73
	v_lshlrev_b32_e32 v86, 4, v100
	v_add3_u32 v0, v73, v86, v0
	v_readlane_b32 s18, v255, 31
	s_add_u32 s18, s18, s4
	v_readlane_b32 s4, v255, 32
	s_waitcnt lgkmcnt(2)
	v_mfma_f32_32x32x16_bf16 v[50:65], v[66:69], v[74:77], v[50:65]
	s_addc_u32 s19, s4, 0
	s_mov_b32 s4, 0
	s_waitcnt lgkmcnt(0)
	v_mfma_f32_32x32x16_bf16 v[34:49], v[82:85], v[74:77], v[34:49]
	v_mfma_f32_32x32x16_bf16 v[2:17], v[82:85], v[78:81], v[2:17]
	v_mfma_f32_32x32x16_bf16 v[18:33], v[66:69], v[78:81], v[18:33]
	ds_read_b128 v[66:69], v101 offset:49152
	ds_read_b128 v[74:77], v102 offset:32768
	ds_read_b128 v[78:81], v102 offset:36864
	ds_read_b128 v[82:85], v101 offset:53248
	s_waitcnt lgkmcnt(2)
	v_mfma_f32_32x32x16_bf16 v[50:65], v[66:69], v[74:77], v[50:65]
	s_waitcnt lgkmcnt(0)
	v_mfma_f32_32x32x16_bf16 v[34:49], v[82:85], v[74:77], v[34:49]
	v_mfma_f32_32x32x16_bf16 v[2:17], v[82:85], v[78:81], v[2:17]
	v_mfma_f32_32x32x16_bf16 v[18:33], v[66:69], v[78:81], v[18:33]
	ds_read_b128 v[66:69], v105 offset:49152
	ds_read_b128 v[74:77], v106 offset:32768
	ds_read_b128 v[78:81], v106 offset:36864
	ds_read_b128 v[82:85], v105 offset:53248
	s_waitcnt lgkmcnt(2)
	v_mfma_f32_32x32x16_bf16 v[50:65], v[66:69], v[74:77], v[50:65]
	s_waitcnt lgkmcnt(0)
	v_mfma_f32_32x32x16_bf16 v[34:49], v[82:85], v[74:77], v[34:49]
	v_mfma_f32_32x32x16_bf16 v[2:17], v[82:85], v[78:81], v[2:17]
	v_mfma_f32_32x32x16_bf16 v[18:33], v[66:69], v[78:81], v[18:33]
	ds_read_b128 v[66:69], v93 offset:49152
	ds_read_b128 v[74:77], v92 offset:32768
	ds_read_b128 v[78:81], v92 offset:36864
	ds_read_b128 v[82:85], v93 offset:53248
	s_waitcnt vmcnt(0)
	s_waitcnt lgkmcnt(0)
	s_barrier
	v_mfma_f32_32x32x16_bf16 v[50:65], v[66:69], v[74:77], v[50:65]
	v_mfma_f32_32x32x16_bf16 v[34:49], v[82:85], v[74:77], v[34:49]
	s_nop 10
	ds_write_b128 v0, v[50:53]
	ds_write_b128 v0, v[54:57] offset:32
	ds_write_b128 v0, v[58:61] offset:64
	ds_write_b128 v0, v[62:65] offset:96
	ds_write_b128 v0, v[34:37] offset:128
	v_mfma_f32_32x32x16_bf16 v[2:17], v[82:85], v[78:81], v[2:17]
	v_mfma_f32_32x32x16_bf16 v[18:33], v[66:69], v[78:81], v[18:33]
	ds_write_b128 v0, v[38:41] offset:160
	ds_write_b128 v0, v[42:45] offset:192
	ds_write_b128 v0, v[46:49] offset:224
	s_nop 8
	ds_write_b128 v0, v[18:21] offset:16896
	ds_write_b128 v0, v[22:25] offset:16928
	ds_write_b128 v0, v[26:29] offset:16960
	ds_write_b128 v0, v[30:33] offset:16992
	ds_write_b128 v0, v[2:5] offset:17024
	ds_write_b128 v0, v[6:9] offset:17056
	ds_write_b128 v0, v[10:13] offset:17088
	ds_write_b128 v0, v[14:17] offset:17120
	v_lshlrev_b32_e32 v0, 2, v71
	v_and_b32_e32 v2, 0x7c, v0
	v_lshlrev_b32_e32 v0, 1, v2
	v_lshl_add_u64 v[6:7], s[18:19], 0, v[0:1]
	v_bfe_u32 v0, v71, 5, 3
	v_or_b32_e32 v14, s2, v0
	v_mul_u32_u24_e32 v0, 0x210, v0
	v_mad_i32_i24 v0, v70, s55, v0
	v_lshlrev_b32_e32 v3, 4, v72
	v_add3_u32 v15, v0, v3, 0
	s_lshl_b32 s2, s5, 1
	v_lshlrev_b32_e32 v8, 1, v2
	s_waitcnt lgkmcnt(0)
	s_barrier
	s_add_u32 s48, s42, s2
	s_addc_u32 s49, s43, 0
	s_add_u32 s48, s48, 0x1000
	s_addc_u32 s49, s49, 0
	v_add_u32_e32 v120, s4, v14
	v_mad_u32_u24 v121, v120, s11, v8
	global_load_dwordx2 v[112:113], v121, s[48:49] offset:704
	v_add_u32_e32 v121, 8, v120
	v_mad_u32_u24 v121, v121, s11, v8
	global_load_dwordx2 v[114:115], v121, s[48:49] offset:704
	v_add_u32_e32 v121, 16, v120
	v_mad_u32_u24 v121, v121, s11, v8
	global_load_dwordx2 v[116:117], v121, s[48:49] offset:704
	v_add_u32_e32 v121, 24, v120
	v_mad_u32_u24 v121, v121, s11, v8
	global_load_dwordx2 v[118:119], v121, s[48:49] offset:704
